# v29 + attention mixer-B unit prologue: first K/V row tile loaded before the Q fragments, Q waited at first use
# baseline (speedup 1.0000x reference)
; template <int MODE, bool FIX> ...
;     ...
;         head = rem >> 4; const int r0 = 4 * (rem & 15), rp = wid >> 2, cgp = wid & 3;
;         qrow = r0 + 2 * rp + (r32 >> 4); qc = 16 * cgp + (r32 & 15); qtok = qrow * 64 + qc; qcol = 768 + head * 64; kcol = 1280 + head * 64; vcol = 1792 + head * 64; ocol = 512 + head * 64;
;         kr_lo = (r0 - 4) > 0 ? (r0 - 4) : 0; const int kr_hi = clampi(r0 - 1, 0, 56) + 7; NTL = kr_hi - kr_lo + 1; lrow0 = b * SEQ + kr_lo * 64;
;         kc0 = clampi(16 * cgp - 8, 0, 32); const int cs = clampi(qc - 8, 0, 48);
;         wa_lo = clampi(r0 + 2 * rp - 4, 0, 56); wa_hi = clampi(r0 + 2 * rp - 3, 0, 56) + 7; rs = clampi(qrow - 4, 0, 56);
; #pragma unroll
;         for (int r = 0; r < 16; ++r) { const int kc = kc0 + (r & 3) + 8 * (r >> 2) + 4 * hi; if ((unsigned)(kc - cs) < 16u) colmask |= (1u << r); }
;         LAS float* rt = (LAS float*)(lds + RPB_OFF);
;         if (tid < 465) rt[tid] = rpb[head * 465 + tid] * LOG2E;
;     }
;     const int NT = NTL + 4, crow0 = ML + b * CTXL;
;     const LAS float* rpbl = (const LAS float*)(lds + RPB_OFF);
;     bf16x8 qf[4];
;     { const bf16_t* qp = QKV + (size_t)(b * SEQ + qtok) * INC + qcol + hi * 8;
; #pragma unroll
;       for (int d0 = 0; d0 < 4; ++d0) qf[d0] = *(const bf16x8*)(qp + d0 * 16); }
;     float m = FIX ? Mb : -INFINITY, l = 0.f;
;     const float ci = FIX ? -Mb : 0.f;
;     const f32x16 cinit = {ci, ci, ci, ci, ci, ci, ci, ci, ci, ci, ci, ci, ci, ci, ci, ci};
;     ...
;         u32x4 kA, vA;
;         { const size_t ro_ = (size_t)ATT_SEQ_ROW(0) * INC; kA = *(const u32x4*)(gk + ro_); vA = *(const u32x4*)(gv + ro_); }
;         int i = 0;
;         for (; i < nmask; ++i) {
;             ATT_STEP_PRE(i)
;             if (MODE == 0) {
;                 const int tl = ATT_SEQ_TL(i); const int dA = 2 * tl - s_sub, dB = dA + 1;
;                 const int a0 = (dA < 0 || dA > 8) ? 99 : (dA == 0 ? 0 : -99), b0 = (dA < 0 || dA > 8) ? -99 : (dA == 8 ? 0 : 99);
;                 const int a1 = (dB < 0 || dB > 8) ? 99 : (dB == 0 ? 0 : -99), b1 = (dB < 0 || dB > 8) ? -99 : (dB == 8 ? 0 : 99);
;                 tile64<true>(buf, qf, o0, o1, l, lane, r32, hi, cinit, a0, b0, a1, b1);
;             } else {
;                 const int kr = kr_lo + i;
;                 const unsigned vm = (kr >= wa_lo && kr <= wa_hi && (unsigned)(kr - rs) < 8u) ? colmask : 0u;
.LBB0_725:
	s_or_b64 exec, exec, s[8:9]
	s_ashr_i32 s8, s15, 7
	s_lshl_b32 s51, s8, 12
	s_lshl_b32 s52, s8, 8
	v_readlane_b32 s8, v255, 20
	v_or_b32_e32 v0, s51, v149
	v_readlane_b32 s9, v255, 21
	v_add_u32_e32 v14, v0, v159
	s_add_i32 s52, s52, 0x8000
	v_mov_b64_e32 v[2:3], s[8:9]
	v_mad_i64_i32 v[2:3], s[8:9], v14, s2, v[2:3]
	s_lshl_b32 s8, s50, 6
	s_or_b32 s10, s16, s51
	s_lshl_b32 s42, s53, 7
	s_add_i32 s11, s8, s52
	s_cmp_lt_i32 s49, 0
	v_lshl_add_u64 v[2:3], v[2:3], 0, s[42:43]
	s_cselect_b64 s[8:9], -1, 0
	v_lshl_add_u64 v[32:33], v[176:177], 1, v[2:3]
	s_and_b64 vcc, s[8:9], exec
	v_lshl_add_u64 v[104:105], v[180:181], 0, s[42:43]
	s_cselect_b32 s8, s11, s10
	v_mad_i64_i32 v[240:241], s[8:9], s8, v156, v[104:105]
	s_nop 1
	global_load_dwordx4 v[96:99], v[240:241], off offset:2560
	global_load_dwordx4 v[100:103], v[240:241], off offset:3584
	global_load_dwordx4 v[2:5], v[32:33], off offset:1536
	global_load_dwordx4 v[6:9], v[32:33], off offset:1568
	global_load_dwordx4 v[10:13], v[32:33], off offset:1600
	global_load_dwordx4 v[92:95], v[32:33], off offset:1632
	s_waitcnt vmcnt(6)
	v_mul_f32_e32 v242, 0x3fb8aa3b, v242
	ds_write_b32 v151, v242
	s_mov_b32 s11, 0
	s_mov_b32 s10, 0
	s_cbranch_vccnz .LBB0_729
	v_sub_co_u32_e64 v0, s[8:9], s13, 3
	v_add_u32_e32 v15, -4, v158
	v_min_u32_e32 v0, 56, v0
	v_min_u32_e32 v15, 56, v15
	v_sub_co_u32_e64 v32, s[16:17], s13, 4
	s_cmp_gt_u32 s13, 3
	v_add_u32_e32 v0, 7, v0
	v_cndmask_b32_e64 v33, v15, 0, s[16:17]
	s_cselect_b64 s[44:45], -1, 0
	v_cndmask_b32_e64 v80, v0, 7, s[8:9]
	s_min_u32 s8, s12, 4
	v_sub_u32_e32 v0, s12, v33
	s_add_i32 s9, s14, s8
	v_subrev_u32_e32 v81, s8, v0
	v_add_u32_e32 v0, s8, v148
	s_sub_i32 s42, s9, s12
	s_sub_i32 s9, s12, s14
	v_mad_i32_i24 v82, v0, s3, v155
	v_mov_b32_e32 v0, 0
	v_min_u32_e32 v15, 56, v32
	s_add_i32 s42, s42, 1
	s_sub_i32 s54, s9, s8
	v_mov_b32_e32 v32, 0
	v_mov_b32_e32 v33, v0
	v_mov_b32_e32 v34, v0
	v_mov_b32_e32 v35, v0
	v_mov_b32_e32 v36, v0
	v_mov_b32_e32 v37, v0
	v_mov_b32_e32 v38, v0
	v_mov_b32_e32 v39, v0
	v_mov_b32_e32 v40, v0
	v_mov_b32_e32 v41, v0
	v_mov_b32_e32 v42, v0
	v_mov_b32_e32 v43, v0
	v_mov_b32_e32 v44, v0
	v_mov_b32_e32 v45, v0
	v_mov_b32_e32 v46, v0
	v_mov_b32_e32 v47, v0
	v_mov_b32_e32 v48, 0
	v_mov_b32_e32 v49, v0
	v_mov_b32_e32 v50, v0
	v_mov_b32_e32 v51, v0
	v_mov_b32_e32 v52, v0
	v_mov_b32_e32 v53, v0
	v_mov_b32_e32 v54, v0
	v_mov_b32_e32 v55, v0
	v_mov_b32_e32 v56, v0
	v_mov_b32_e32 v57, v0
	v_mov_b32_e32 v58, v0
	v_mov_b32_e32 v59, v0
	v_mov_b32_e32 v60, v0
	v_mov_b32_e32 v61, v0
	v_mov_b32_e32 v62, v0
	v_mov_b32_e32 v63, v0
	s_mov_b32 s36, 1
	s_waitcnt vmcnt(4)
.LBB0_727:
	s_bitcmp1_b32 s10, 0
	s_cselect_b32 s8, 0x4480, 0
	s_add_i32 s13, s48, s10
	v_add_u32_e32 v64, s10, v81
	s_add_i32 s55, s10, 1
	s_add_i32 s11, s54, s10
	s_add_i32 s14, s8, 0
	s_add_i32 s12, s13, 1
	v_cmp_gt_u32_e32 vcc, 8, v64
	v_cmp_lt_u32_e64 s[8:9], s13, v15
	s_cmp_lt_i32 s10, s49
	v_cndmask_b32_e32 v212, v230, v82, vcc
	v_cmp_gt_u32_e32 vcc, s13, v80
	s_cselect_b32 s10, s12, s11
	s_cselect_b32 s11, s51, s52
	s_and_b64 s[8:9], s[44:45], s[8:9]
	v_add_u32_e32 v65, s14, v178
	s_lshl_b32 s10, s10, 6
	s_or_b64 s[8:9], s[8:9], vcc
	v_add_u32_e32 v66, s14, v194
	s_cmp_lg_u32 s36, 0
	s_cbranch_scc1 .Lb_nw1
	s_waitcnt vmcnt(0)
; #define LAS __attribute__((address_space(3)))
; template <int MASK, bool FIX> ...
;     const LAS unsigned char* kp = buf + (kvoff + r32) * KSTR + hi * 16;
;     f32x16 s = cinit;
; #pragma unroll
;     for (int d0 = 0; d0 < 4; ++d0) { const bf16x8 kf = *(const LAS bf16x8*)(kp + d0 * 32); s = __builtin_amdgcn_mfma_f32_32x32x16_bf16(kf, qf[d0], s, 0, 0, 0); }
;     const float NEG = -INFINITY;
;     if (MASK == 3) {
;         float bv[16];
; #pragma unroll
;         for (int r = 0; r < 16; ++r) bv[r] = rpbl[bidx0 + (r & 3) + 8 * (r >> 2)];
; #pragma unroll
;         for (int r = 0; r < 16; ++r) asm volatile("" : "+v"(bv[r]));
; #pragma unroll
;         for (int r = 0; r < 16; ++r) s[r] = ((vmask >> r) & 1u) ? (s[r] + bv[r]) : NEG;
;     }
; #pragma unroll
;     for (int r = 0; r < 16; ++r) {
;         const int kl0 = (r & 3) + 8 * (r >> 2);
;         if (MASK == 1) { if (kl0 + 4 * hi < r32) s[r] = NEG; }
;         if (MASK == 2) { if (kl0 + 4 * hi > r32) s[r] = NEG; }
;     }
;     if (!FIX) {
;         float mx = fmaxf(fmaxf(s[0], s[1]), fmaxf(s[2], s[3]));
; #pragma unroll
;         for (int r = 4; r < 16; r += 4) mx = fmaxf(mx, fmaxf(fmaxf(s[r], s[r + 1]), fmaxf(s[r + 2], s[r + 3])));
;         mx = swap_max(mx);
;         const float mnew = fmaxf(m, mx);
; template <int MODE, bool FIX> ...
;     ...
;         u32x4 kA, vA;
;         { const size_t ro_ = (size_t)ATT_SEQ_ROW(0) * INC; kA = *(const u32x4*)(gk + ro_); vA = *(const u32x4*)(gv + ro_); }
;         int i = 0;
;         for (; i < nmask; ++i) {
;             ATT_STEP_PRE(i)
;             if (MODE == 0) {
;                 const int tl = ATT_SEQ_TL(i); const int dA = 2 * tl - s_sub, dB = dA + 1;
;                 const int a0 = (dA < 0 || dA > 8) ? 99 : (dA == 0 ? 0 : -99), b0 = (dA < 0 || dA > 8) ? -99 : (dA == 8 ? 0 : 99);
;                 const int a1 = (dB < 0 || dB > 8) ? 99 : (dB == 0 ? 0 : -99), b1 = (dB < 0 || dB > 8) ? -99 : (dB == 8 ? 0 : 99);
;                 tile64<true>(buf, qf, o0, o1, l, lane, r32, hi, cinit, a0, b0, a1, b1);
;             } else {
;                 const int kr = kr_lo + i;
;                 const unsigned vm = (kr >= wa_lo && kr <= wa_hi && (unsigned)(kr - rs) < 8u) ? colmask : 0u;
;                 const int bidx0 = (kr - qrow + 7) * 31 + kc0 + 4 * hi - qc + 15;
;                 half_step<3, true>(buf, kc0, qf, o0, o1, m, l, lane, r32, hi, rpbl, bidx0, vm, cinit);
.Lb_nw1:
	s_mov_b32 s36, 0
	ds_write_b128 v65, v[96:99]
	ds_write_b128 v66, v[100:103] offset:9216
	v_cndmask_b32_e64 v212, v212, v230, s[8:9]
	s_add_i32 s10, s10, s11
	v_add3_u32 v67, s14, v152, v189
	v_mad_i64_i32 v[240:241], s[8:9], s10, v156, v[104:105]
	s_nop 1
	global_load_dwordx4 v[96:99], v[240:241], off offset:2560
	global_load_dwordx4 v[100:103], v[240:241], off offset:3584
	s_waitcnt lgkmcnt(0)
	s_barrier
	v_cmp_eq_u32_e64 s[8:9], v212, v230
	s_nop 1
	s_cmp_eq_u64 s[8:9], exec
	s_cbranch_scc1 .Lmb_skip
	ds_read_b128 v[84:87], v67
	ds_read_b128 v[88:91], v67 offset:32
	ds_read_b128 v[106:109], v67 offset:64
	ds_read_b128 v[110:113], v67 offset:96
	ds_read2_b32 v[118:119], v212 offset1:1
	ds_read2_b32 v[120:121], v212 offset0:2 offset1:3
	ds_read2_b32 v[122:123], v212 offset0:8 offset1:9
	ds_read2_b32 v[124:125], v212 offset0:10 offset1:11
	ds_read2_b32 v[126:127], v212 offset0:16 offset1:17
	ds_read2_b32 v[128:129], v212 offset0:18 offset1:19
	ds_read2_b32 v[130:131], v212 offset0:24 offset1:25
	s_waitcnt lgkmcnt(13)
	ds_read2_b32 v[132:133], v212 offset0:26 offset1:27
	v_add3_u32 v68, s14, v190, v153
	v_add3_u32 v83, v68, v191, v192
	s_waitcnt lgkmcnt(11)
	s_waitcnt vmcnt(2)
	v_mfma_f32_32x32x16_bf16 v[64:79], v[84:87], v[2:5], v[196:211]
	s_waitcnt lgkmcnt(7)
	s_waitcnt lgkmcnt(6)
	s_waitcnt lgkmcnt(5)
	s_waitcnt lgkmcnt(4)
	v_mfma_f32_32x32x16_bf16 v[64:79], v[88:91], v[6:9], v[64:79]
	s_waitcnt lgkmcnt(3)
	s_waitcnt lgkmcnt(2)
	s_waitcnt lgkmcnt(1)
	v_mfma_f32_32x32x16_bf16 v[64:79], v[106:109], v[10:13], v[64:79]
	s_waitcnt lgkmcnt(0)
	ds_read_b64_tr_b16 v[84:85], v83 offset:9216
	v_mfma_f32_32x32x16_bf16 v[64:79], v[110:113], v[92:95], v[64:79]
	ds_read_b64_tr_b16 v[86:87], v83 offset:9728
	ds_read_b64_tr_b16 v[88:89], v83 offset:10240
	ds_read_b64_tr_b16 v[90:91], v83 offset:10752
	ds_read_b64_tr_b16 v[106:107], v83 offset:13376
	ds_read_b64_tr_b16 v[108:109], v83 offset:13888
	ds_read_b64_tr_b16 v[114:115], v83 offset:14400
	ds_read_b64_tr_b16 v[116:117], v83 offset:14912
	s_nop 5
	v_pk_add_f32 v[214:215], v[118:119], v[64:65]
	v_pk_add_f32 v[216:217], v[120:121], v[66:67]
	v_pk_add_f32 v[218:219], v[122:123], v[68:69]
	v_pk_add_f32 v[220:221], v[124:125], v[70:71]
	v_pk_add_f32 v[222:223], v[126:127], v[72:73]
	v_pk_add_f32 v[224:225], v[128:129], v[74:75]
	v_pk_add_f32 v[226:227], v[130:131], v[76:77]
	v_pk_add_f32 v[228:229], v[132:133], v[78:79]
	v_exp_f32_e32 v68, v214
	v_exp_f32_e32 v70, v215
	v_exp_f32_e32 v72, v216
	v_exp_f32_e32 v74, v217
	v_exp_f32_e32 v76, v218
	v_exp_f32_e32 v78, v219
	v_exp_f32_e32 v110, v220
	v_exp_f32_e32 v112, v221
	v_cvt_pk_bf16_f32 v64, v68, v70
	v_cvt_pk_bf16_f32 v65, v72, v74
	v_cvt_pk_bf16_f32 v66, v76, v78
	v_cvt_pk_bf16_f32 v67, v110, v112
	s_nop 0
	s_waitcnt lgkmcnt(6)
	v_mfma_f32_32x32x16_bf16 v[32:47], v[84:87], v[64:67], v[32:47]
	s_waitcnt lgkmcnt(2)
	v_mfma_f32_32x32x16_bf16 v[48:63], v[106:109], v[64:67], v[48:63]
	v_exp_f32_e32 v69, v222
	v_exp_f32_e32 v71, v223
	v_exp_f32_e32 v73, v224
	v_exp_f32_e32 v75, v225
	v_exp_f32_e32 v77, v226
	v_exp_f32_e32 v79, v227
	v_exp_f32_e32 v111, v228
	v_exp_f32_e32 v113, v229
	v_cvt_pk_bf16_f32 v64, v69, v71
	v_cvt_pk_bf16_f32 v65, v73, v75
	v_cvt_pk_bf16_f32 v66, v77, v79
	v_cvt_pk_bf16_f32 v67, v111, v113
	v_pk_add_f32 v[68:69], v[68:69], v[70:71]
	v_pk_add_f32 v[72:73], v[72:73], v[74:75]
	v_mfma_f32_32x32x16_bf16 v[32:47], v[88:91], v[64:67], v[32:47]
	v_pk_add_f32 v[76:77], v[76:77], v[78:79]
	v_pk_add_f32 v[110:111], v[110:111], v[112:113]
	s_mov_b32 s10, s55
	v_add_u32_e32 v82, 0x7c, v82
	s_cmp_eq_u32 s42, s55
	s_waitcnt lgkmcnt(0)
	v_mfma_f32_32x32x16_bf16 v[48:63], v[114:117], v[64:67], v[48:63]
	v_pk_add_f32 v[68:69], v[68:69], v[72:73]
	v_pk_add_f32 v[76:77], v[76:77], v[110:111]
	s_nop 0
	v_pk_add_f32 v[68:69], v[68:69], v[76:77]
	s_nop 0
	v_add_f32_e32 v64, v68, v69
	v_add_f32_e32 v0, v0, v64
	s_cbranch_scc0 .LBB0_727
	s_branch .Lmb_done
